# hyena filter MLP trunk: weight loads of each dot product requested in one or two batches instead of 11/16 dependent rounds (same fma order)
# speedup vs baseline: 1.0086x; 1.0018x over previous
.LBB0_74:
	global_load_dword v100, v[18:19], off offset:-256
	global_load_dword v101, v[18:19], off
	global_load_dword v102, v[18:19], off offset:256
	v_lshl_add_u64 v[18:19], v[18:19], 0, s[70:71]
	global_load_dword v103, v[18:19], off offset:-256
	global_load_dword v104, v[18:19], off
	global_load_dword v105, v[18:19], off offset:256
	v_lshl_add_u64 v[18:19], v[18:19], 0, s[70:71]
	global_load_dword v106, v[18:19], off offset:-256
	global_load_dword v107, v[18:19], off
	global_load_dword v108, v[18:19], off offset:256
	v_lshl_add_u64 v[18:19], v[18:19], 0, s[70:71]
	global_load_dword v109, v[18:19], off offset:-256
	global_load_dword v110, v[18:19], off
	global_load_dword v111, v[18:19], off offset:256
	v_lshl_add_u64 v[18:19], v[18:19], 0, s[70:71]
	global_load_dword v112, v[18:19], off offset:-256
	global_load_dword v113, v[18:19], off
	global_load_dword v114, v[18:19], off offset:256
	v_lshl_add_u64 v[18:19], v[18:19], 0, s[70:71]
	global_load_dword v115, v[18:19], off offset:-256
	global_load_dword v116, v[18:19], off
	global_load_dword v117, v[18:19], off offset:256
	v_lshl_add_u64 v[18:19], v[18:19], 0, s[70:71]
	global_load_dword v118, v[18:19], off offset:-256
	global_load_dword v119, v[18:19], off
	global_load_dword v120, v[18:19], off offset:256
	v_lshl_add_u64 v[18:19], v[18:19], 0, s[70:71]
	global_load_dword v121, v[18:19], off offset:-256
	global_load_dword v122, v[18:19], off
	global_load_dword v123, v[18:19], off offset:256
	v_lshl_add_u64 v[18:19], v[18:19], 0, s[70:71]
	global_load_dword v124, v[18:19], off offset:-256
	global_load_dword v125, v[18:19], off
	global_load_dword v126, v[18:19], off offset:256
	v_lshl_add_u64 v[18:19], v[18:19], 0, s[70:71]
	global_load_dword v127, v[18:19], off offset:-256
	global_load_dword v128, v[18:19], off
	global_load_dword v129, v[18:19], off offset:256
	v_lshl_add_u64 v[18:19], v[18:19], 0, s[70:71]
	global_load_dword v130, v[18:19], off offset:-256
	global_load_dword v131, v[18:19], off
	global_load_dword v132, v[18:19], off offset:256
	v_lshl_add_u64 v[18:19], v[18:19], 0, s[70:71]
	ds_read2_b32 v[32:33], v26 offset0:0 offset1:1
	ds_read_b32 v36, v26 offset:8
	ds_read2_b32 v[164:165], v26 offset0:3 offset1:4
	ds_read_b32 v166, v26 offset:20
	s_waitcnt vmcnt(32) lgkmcnt(3)
	v_fmac_f32_e32 v17, v32, v100
	s_waitcnt vmcnt(31)
	v_fmac_f32_e32 v17, v33, v101
	s_waitcnt vmcnt(30) lgkmcnt(2)
	v_fmac_f32_e32 v17, v36, v102
	ds_read2_b32 v[32:33], v26 offset0:6 offset1:7
	ds_read_b32 v36, v26 offset:32
	s_waitcnt vmcnt(29) lgkmcnt(3)
	v_fmac_f32_e32 v17, v164, v103
	s_waitcnt vmcnt(28)
	v_fmac_f32_e32 v17, v165, v104
	s_waitcnt vmcnt(27) lgkmcnt(2)
	v_fmac_f32_e32 v17, v166, v105
	ds_read2_b32 v[164:165], v26 offset0:9 offset1:10
	ds_read_b32 v166, v26 offset:44
	s_waitcnt vmcnt(26) lgkmcnt(3)
	v_fmac_f32_e32 v17, v32, v106
	s_waitcnt vmcnt(25)
	v_fmac_f32_e32 v17, v33, v107
	s_waitcnt vmcnt(24) lgkmcnt(2)
	v_fmac_f32_e32 v17, v36, v108
	ds_read2_b32 v[32:33], v26 offset0:12 offset1:13
	ds_read_b32 v36, v26 offset:56
	s_waitcnt vmcnt(23) lgkmcnt(3)
	v_fmac_f32_e32 v17, v164, v109
	s_waitcnt vmcnt(22)
	v_fmac_f32_e32 v17, v165, v110
	s_waitcnt vmcnt(21) lgkmcnt(2)
	v_fmac_f32_e32 v17, v166, v111
	ds_read2_b32 v[164:165], v26 offset0:15 offset1:16
	ds_read_b32 v166, v26 offset:68
	s_waitcnt vmcnt(20) lgkmcnt(3)
	v_fmac_f32_e32 v17, v32, v112
	s_waitcnt vmcnt(19)
	v_fmac_f32_e32 v17, v33, v113
	s_waitcnt vmcnt(18) lgkmcnt(2)
	v_fmac_f32_e32 v17, v36, v114
	ds_read2_b32 v[32:33], v26 offset0:18 offset1:19
	ds_read_b32 v36, v26 offset:80
	s_waitcnt vmcnt(17) lgkmcnt(3)
	v_fmac_f32_e32 v17, v164, v115
	s_waitcnt vmcnt(16)
	v_fmac_f32_e32 v17, v165, v116
	s_waitcnt vmcnt(15) lgkmcnt(2)
	v_fmac_f32_e32 v17, v166, v117
	ds_read2_b32 v[164:165], v26 offset0:21 offset1:22
	ds_read_b32 v166, v26 offset:92
	s_waitcnt vmcnt(14) lgkmcnt(3)
	v_fmac_f32_e32 v17, v32, v118
	s_waitcnt vmcnt(13)
	v_fmac_f32_e32 v17, v33, v119
	s_waitcnt vmcnt(12) lgkmcnt(2)
	v_fmac_f32_e32 v17, v36, v120
	ds_read2_b32 v[32:33], v26 offset0:24 offset1:25
	ds_read_b32 v36, v26 offset:104
	s_waitcnt vmcnt(11) lgkmcnt(3)
	v_fmac_f32_e32 v17, v164, v121
	s_waitcnt vmcnt(10)
	v_fmac_f32_e32 v17, v165, v122
	s_waitcnt vmcnt(9) lgkmcnt(2)
	v_fmac_f32_e32 v17, v166, v123
	ds_read2_b32 v[164:165], v26 offset0:27 offset1:28
	ds_read_b32 v166, v26 offset:116
	s_waitcnt vmcnt(8) lgkmcnt(3)
	v_fmac_f32_e32 v17, v32, v124
	s_waitcnt vmcnt(7)
	v_fmac_f32_e32 v17, v33, v125
	s_waitcnt vmcnt(6) lgkmcnt(2)
	v_fmac_f32_e32 v17, v36, v126
	ds_read2_b32 v[32:33], v26 offset0:30 offset1:31
	ds_read_b32 v36, v26 offset:128
	s_waitcnt vmcnt(5) lgkmcnt(3)
	v_fmac_f32_e32 v17, v164, v127
	s_waitcnt vmcnt(4)
	v_fmac_f32_e32 v17, v165, v128
	s_waitcnt vmcnt(3) lgkmcnt(2)
	v_fmac_f32_e32 v17, v166, v129
	s_waitcnt vmcnt(2) lgkmcnt(1)
	v_fmac_f32_e32 v17, v32, v130
	s_waitcnt vmcnt(1)
	v_fmac_f32_e32 v17, v33, v131
	s_waitcnt vmcnt(0) lgkmcnt(0)
	v_fmac_f32_e32 v17, v36, v132
	s_movk_i32 s0, 0x84
	v_and_b32_e32 v18, 0x7fffffff, v17
	v_cmp_nlt_f32_e64 s[0:1], |v17|, s65
	s_and_saveexec_b64 s[10:11], s[0:1]
	s_xor_b64 s[86:87], exec, s[10:11]
	s_cbranch_execz .LBB0_77
	v_lshrrev_b32_e32 v2, 23, v18
	v_add_u32_e32 v2, 0xffffff88, v2
	v_cmp_lt_u32_e64 s[0:1], 63, v2
	s_nop 1
	v_cndmask_b32_e64 v19, 0, v23, s[0:1]
	v_add_u32_e32 v2, v19, v2
	v_cmp_lt_u32_e64 s[10:11], 31, v2
	s_nop 1
	v_cndmask_b32_e64 v19, 0, v24, s[10:11]
	v_add_u32_e32 v2, v19, v2
	v_cmp_lt_u32_e64 s[12:13], 31, v2
	s_nop 1
	v_cndmask_b32_e64 v19, 0, v24, s[12:13]
	v_add_u32_e32 v19, v19, v2
	v_and_b32_e32 v2, 0x7fffff, v18
	v_or_b32_e32 v44, 0x800000, v2
	v_mad_u64_u32 v[32:33], s[14:15], v44, s66, 0
	v_mov_b32_e32 v2, v33
	v_mad_u64_u32 v[34:35], s[14:15], v44, s67, v[2:3]
	v_mov_b32_e32 v2, v35
	v_mad_u64_u32 v[36:37], s[14:15], v44, s68, v[2:3]
	v_mov_b32_e32 v2, v37
	v_mad_u64_u32 v[38:39], s[14:15], v44, s69, v[2:3]
	v_mov_b32_e32 v2, v39
	v_mad_u64_u32 v[40:41], s[14:15], v44, s54, v[2:3]
	v_mov_b32_e32 v2, v41
	v_mad_u64_u32 v[42:43], s[14:15], v44, s78, v[2:3]
	v_mov_b32_e32 v2, v43
	v_mad_u64_u32 v[44:45], s[14:15], v44, s30, v[2:3]
	v_cndmask_b32_e64 v33, v42, v38, s[0:1]
	v_cndmask_b32_e64 v2, v44, v40, s[0:1]
	v_cndmask_b32_e64 v37, v45, v42, s[0:1]
	v_cndmask_b32_e64 v35, v2, v33, s[10:11]
	v_cndmask_b32_e64 v2, v37, v2, s[10:11]
	v_cndmask_b32_e64 v37, v40, v36, s[0:1]
	v_cndmask_b32_e64 v33, v33, v37, s[10:11]
	v_sub_u32_e32 v39, 32, v19
	v_cmp_eq_u32_e64 s[14:15], 0, v19
	v_cndmask_b32_e64 v19, v38, v34, s[0:1]
	v_cndmask_b32_e64 v2, v2, v35, s[12:13]
	v_cndmask_b32_e64 v35, v35, v33, s[12:13]
	v_cndmask_b32_e64 v34, v37, v19, s[10:11]
	v_alignbit_b32 v40, v2, v35, v39
	v_cndmask_b32_e64 v33, v33, v34, s[12:13]
	v_cndmask_b32_e64 v2, v40, v2, s[14:15]
	v_alignbit_b32 v37, v35, v33, v39
	v_cndmask_b32_e64 v32, v36, v32, s[0:1]
	v_cndmask_b32_e64 v35, v37, v35, s[14:15]
	v_bfe_u32 v40, v2, 29, 1
	v_cndmask_b32_e64 v19, v19, v32, s[10:11]
	v_alignbit_b32 v37, v2, v35, 30
	v_sub_u32_e32 v41, 0, v40
	v_cndmask_b32_e64 v19, v34, v19, s[12:13]
	v_xor_b32_e32 v37, v37, v41
	v_alignbit_b32 v32, v33, v19, v39
	v_cndmask_b32_e64 v32, v32, v33, s[14:15]
	v_ffbh_u32_e32 v34, v37
	v_alignbit_b32 v33, v35, v32, 30
	v_min_u32_e32 v34, 32, v34
	v_alignbit_b32 v19, v32, v19, 30
	v_xor_b32_e32 v33, v33, v41
	v_sub_u32_e32 v35, 31, v34
	v_xor_b32_e32 v19, v19, v41
	v_alignbit_b32 v36, v37, v33, v35
	v_alignbit_b32 v19, v33, v19, v35
	v_alignbit_b32 v32, v36, v19, 9
	v_ffbh_u32_e32 v33, v32
	v_min_u32_e32 v33, 32, v33
	v_lshrrev_b32_e32 v38, 29, v2
	v_not_b32_e32 v35, v33
	v_alignbit_b32 v19, v32, v19, v35
	v_lshlrev_b32_e32 v32, 31, v38
	v_or_b32_e32 v35, 0x33000000, v32
	v_add_lshl_u32 v33, v33, v34, 23
	v_lshrrev_b32_e32 v19, 9, v19
	v_sub_u32_e32 v33, v35, v33
	v_or_b32_e32 v32, 0.5, v32
	v_lshlrev_b32_e32 v34, 23, v34
	v_or_b32_e32 v19, v33, v19
	v_lshrrev_b32_e32 v33, 9, v36
	v_sub_u32_e32 v32, v32, v34
	v_or_b32_e32 v32, v33, v32
	v_mul_f32_e32 v33, 0x3fc90fda, v32
	v_fma_f32 v34, v32, s31, -v33
	v_fmac_f32_e32 v34, 0x33a22168, v32
	v_fmac_f32_e32 v34, 0x3fc90fda, v19
	v_lshrrev_b32_e32 v2, 30, v2
	v_add_f32_e32 v19, v33, v34
	v_add_u32_e32 v2, v40, v2

.LBB0_82:
	global_load_dword v100, v[18:19], off offset:-512
	global_load_dword v101, v[18:19], off offset:-256
	global_load_dword v102, v[18:19], off
	global_load_dword v103, v[18:19], off offset:256
	v_lshl_add_u64 v[18:19], v[18:19], 0, s[80:81]
	global_load_dword v104, v[18:19], off offset:-512
	global_load_dword v105, v[18:19], off offset:-256
	global_load_dword v106, v[18:19], off
	global_load_dword v107, v[18:19], off offset:256
	v_lshl_add_u64 v[18:19], v[18:19], 0, s[80:81]
	global_load_dword v108, v[18:19], off offset:-512
	global_load_dword v109, v[18:19], off offset:-256
	global_load_dword v110, v[18:19], off
	global_load_dword v111, v[18:19], off offset:256
	v_lshl_add_u64 v[18:19], v[18:19], 0, s[80:81]
	global_load_dword v112, v[18:19], off offset:-512
	global_load_dword v113, v[18:19], off offset:-256
	global_load_dword v114, v[18:19], off
	global_load_dword v115, v[18:19], off offset:256
	v_lshl_add_u64 v[18:19], v[18:19], 0, s[80:81]
	global_load_dword v116, v[18:19], off offset:-512
	global_load_dword v117, v[18:19], off offset:-256
	global_load_dword v118, v[18:19], off
	global_load_dword v119, v[18:19], off offset:256
	v_lshl_add_u64 v[18:19], v[18:19], 0, s[80:81]
	global_load_dword v120, v[18:19], off offset:-512
	global_load_dword v121, v[18:19], off offset:-256
	global_load_dword v122, v[18:19], off
	global_load_dword v123, v[18:19], off offset:256
	v_lshl_add_u64 v[18:19], v[18:19], 0, s[80:81]
	global_load_dword v124, v[18:19], off offset:-512
	global_load_dword v125, v[18:19], off offset:-256
	global_load_dword v126, v[18:19], off
	global_load_dword v127, v[18:19], off offset:256
	v_lshl_add_u64 v[18:19], v[18:19], 0, s[80:81]
	global_load_dword v128, v[18:19], off offset:-512
	global_load_dword v129, v[18:19], off offset:-256
	global_load_dword v130, v[18:19], off
	global_load_dword v131, v[18:19], off offset:256
	v_lshl_add_u64 v[18:19], v[18:19], 0, s[80:81]
	ds_read_b128 v[32:35], v30 offset:0
	ds_read_b128 v[164:167], v30 offset:16
	s_waitcnt vmcnt(31) lgkmcnt(1)
	v_fmac_f32_e32 v17, v32, v100
	s_waitcnt vmcnt(30)
	v_fmac_f32_e32 v17, v33, v101
	s_waitcnt vmcnt(29)
	v_fmac_f32_e32 v17, v34, v102
	s_waitcnt vmcnt(28)
	v_fmac_f32_e32 v17, v35, v103
	ds_read_b128 v[32:35], v30 offset:32
	s_waitcnt vmcnt(27) lgkmcnt(1)
	v_fmac_f32_e32 v17, v164, v104
	s_waitcnt vmcnt(26)
	v_fmac_f32_e32 v17, v165, v105
	s_waitcnt vmcnt(25)
	v_fmac_f32_e32 v17, v166, v106
	s_waitcnt vmcnt(24)
	v_fmac_f32_e32 v17, v167, v107
	ds_read_b128 v[164:167], v30 offset:48
	s_waitcnt vmcnt(23) lgkmcnt(1)
	v_fmac_f32_e32 v17, v32, v108
	s_waitcnt vmcnt(22)
	v_fmac_f32_e32 v17, v33, v109
	s_waitcnt vmcnt(21)
	v_fmac_f32_e32 v17, v34, v110
	s_waitcnt vmcnt(20)
	v_fmac_f32_e32 v17, v35, v111
	ds_read_b128 v[32:35], v30 offset:64
	s_waitcnt vmcnt(19) lgkmcnt(1)
	v_fmac_f32_e32 v17, v164, v112
	s_waitcnt vmcnt(18)
	v_fmac_f32_e32 v17, v165, v113
	s_waitcnt vmcnt(17)
	v_fmac_f32_e32 v17, v166, v114
	s_waitcnt vmcnt(16)
	v_fmac_f32_e32 v17, v167, v115
	ds_read_b128 v[164:167], v30 offset:80
	s_waitcnt vmcnt(15) lgkmcnt(1)
	v_fmac_f32_e32 v17, v32, v116
	s_waitcnt vmcnt(14)
	v_fmac_f32_e32 v17, v33, v117
	s_waitcnt vmcnt(13)
	v_fmac_f32_e32 v17, v34, v118
	s_waitcnt vmcnt(12)
	v_fmac_f32_e32 v17, v35, v119
	ds_read_b128 v[32:35], v30 offset:96
	s_waitcnt vmcnt(11) lgkmcnt(1)
	v_fmac_f32_e32 v17, v164, v120
	s_waitcnt vmcnt(10)
	v_fmac_f32_e32 v17, v165, v121
	s_waitcnt vmcnt(9)
	v_fmac_f32_e32 v17, v166, v122
	s_waitcnt vmcnt(8)
	v_fmac_f32_e32 v17, v167, v123
	ds_read_b128 v[164:167], v30 offset:112
	s_waitcnt vmcnt(7) lgkmcnt(1)
	v_fmac_f32_e32 v17, v32, v124
	s_waitcnt vmcnt(6)
	v_fmac_f32_e32 v17, v33, v125
	s_waitcnt vmcnt(5)
	v_fmac_f32_e32 v17, v34, v126
	s_waitcnt vmcnt(4)
	v_fmac_f32_e32 v17, v35, v127
	s_waitcnt vmcnt(3) lgkmcnt(0)
	v_fmac_f32_e32 v17, v164, v128
	s_waitcnt vmcnt(2)
	v_fmac_f32_e32 v17, v165, v129
	s_waitcnt vmcnt(1)
	v_fmac_f32_e32 v17, v166, v130
	s_waitcnt vmcnt(0)
	v_fmac_f32_e32 v17, v167, v131
	global_load_dword v100, v[18:19], off offset:-512
	global_load_dword v101, v[18:19], off offset:-256
	global_load_dword v102, v[18:19], off
	global_load_dword v103, v[18:19], off offset:256
	v_lshl_add_u64 v[18:19], v[18:19], 0, s[80:81]
	global_load_dword v104, v[18:19], off offset:-512
	global_load_dword v105, v[18:19], off offset:-256
	global_load_dword v106, v[18:19], off
	global_load_dword v107, v[18:19], off offset:256
	v_lshl_add_u64 v[18:19], v[18:19], 0, s[80:81]
	global_load_dword v108, v[18:19], off offset:-512
	global_load_dword v109, v[18:19], off offset:-256
	global_load_dword v110, v[18:19], off
	global_load_dword v111, v[18:19], off offset:256
	v_lshl_add_u64 v[18:19], v[18:19], 0, s[80:81]
	global_load_dword v112, v[18:19], off offset:-512
	global_load_dword v113, v[18:19], off offset:-256
	global_load_dword v114, v[18:19], off
	global_load_dword v115, v[18:19], off offset:256
	v_lshl_add_u64 v[18:19], v[18:19], 0, s[80:81]
	global_load_dword v116, v[18:19], off offset:-512
	global_load_dword v117, v[18:19], off offset:-256
	global_load_dword v118, v[18:19], off
	global_load_dword v119, v[18:19], off offset:256
	v_lshl_add_u64 v[18:19], v[18:19], 0, s[80:81]
	global_load_dword v120, v[18:19], off offset:-512
	global_load_dword v121, v[18:19], off offset:-256
	global_load_dword v122, v[18:19], off
	global_load_dword v123, v[18:19], off offset:256
	v_lshl_add_u64 v[18:19], v[18:19], 0, s[80:81]
	global_load_dword v124, v[18:19], off offset:-512
	global_load_dword v125, v[18:19], off offset:-256
	global_load_dword v126, v[18:19], off
	global_load_dword v127, v[18:19], off offset:256
	v_lshl_add_u64 v[18:19], v[18:19], 0, s[80:81]
	global_load_dword v128, v[18:19], off offset:-512
	global_load_dword v129, v[18:19], off offset:-256
	global_load_dword v130, v[18:19], off
	global_load_dword v131, v[18:19], off offset:256
	v_lshl_add_u64 v[18:19], v[18:19], 0, s[80:81]
	ds_read_b128 v[32:35], v30 offset:128
	ds_read_b128 v[164:167], v30 offset:144
	s_waitcnt vmcnt(31) lgkmcnt(1)
	v_fmac_f32_e32 v17, v32, v100
	s_waitcnt vmcnt(30)
	v_fmac_f32_e32 v17, v33, v101
	s_waitcnt vmcnt(29)
	v_fmac_f32_e32 v17, v34, v102
	s_waitcnt vmcnt(28)
	v_fmac_f32_e32 v17, v35, v103
	ds_read_b128 v[32:35], v30 offset:160
	s_waitcnt vmcnt(27) lgkmcnt(1)
	v_fmac_f32_e32 v17, v164, v104
	s_waitcnt vmcnt(26)
	v_fmac_f32_e32 v17, v165, v105
	s_waitcnt vmcnt(25)
	v_fmac_f32_e32 v17, v166, v106
	s_waitcnt vmcnt(24)
	v_fmac_f32_e32 v17, v167, v107
	ds_read_b128 v[164:167], v30 offset:176
	s_waitcnt vmcnt(23) lgkmcnt(1)
	v_fmac_f32_e32 v17, v32, v108
	s_waitcnt vmcnt(22)
	v_fmac_f32_e32 v17, v33, v109
	s_waitcnt vmcnt(21)
	v_fmac_f32_e32 v17, v34, v110
	s_waitcnt vmcnt(20)
	v_fmac_f32_e32 v17, v35, v111
	ds_read_b128 v[32:35], v30 offset:192
	s_waitcnt vmcnt(19) lgkmcnt(1)
	v_fmac_f32_e32 v17, v164, v112
	s_waitcnt vmcnt(18)
	v_fmac_f32_e32 v17, v165, v113
	s_waitcnt vmcnt(17)
	v_fmac_f32_e32 v17, v166, v114
	s_waitcnt vmcnt(16)
	v_fmac_f32_e32 v17, v167, v115
	ds_read_b128 v[164:167], v30 offset:208
	s_waitcnt vmcnt(15) lgkmcnt(1)
	v_fmac_f32_e32 v17, v32, v116
	s_waitcnt vmcnt(14)
	v_fmac_f32_e32 v17, v33, v117
	s_waitcnt vmcnt(13)
	v_fmac_f32_e32 v17, v34, v118
	s_waitcnt vmcnt(12)
	v_fmac_f32_e32 v17, v35, v119
	ds_read_b128 v[32:35], v30 offset:224
	s_waitcnt vmcnt(11) lgkmcnt(1)
	v_fmac_f32_e32 v17, v164, v120
	s_waitcnt vmcnt(10)
	v_fmac_f32_e32 v17, v165, v121
	s_waitcnt vmcnt(9)
	v_fmac_f32_e32 v17, v166, v122
	s_waitcnt vmcnt(8)
	v_fmac_f32_e32 v17, v167, v123
	ds_read_b128 v[164:167], v30 offset:240
	s_waitcnt vmcnt(7) lgkmcnt(1)
	v_fmac_f32_e32 v17, v32, v124
	s_waitcnt vmcnt(6)
	v_fmac_f32_e32 v17, v33, v125
	s_waitcnt vmcnt(5)
	v_fmac_f32_e32 v17, v34, v126
	s_waitcnt vmcnt(4)
	v_fmac_f32_e32 v17, v35, v127
	s_waitcnt vmcnt(3) lgkmcnt(0)
	v_fmac_f32_e32 v17, v164, v128
	s_waitcnt vmcnt(2)
	v_fmac_f32_e32 v17, v165, v129
	s_waitcnt vmcnt(1)
	v_fmac_f32_e32 v17, v166, v130
	s_waitcnt vmcnt(0)
	v_fmac_f32_e32 v17, v167, v131
	s_movk_i32 s0, 0x100
	v_and_b32_e32 v18, 0x7fffffff, v17
	v_cmp_nlt_f32_e64 s[0:1], |v17|, s65
	s_and_saveexec_b64 s[10:11], s[0:1]
	s_xor_b64 s[86:87], exec, s[10:11]
	s_cbranch_execz .LBB0_85
	v_lshrrev_b32_e32 v2, 23, v18
	v_add_u32_e32 v2, 0xffffff88, v2
	v_cmp_lt_u32_e64 s[0:1], 63, v2
	s_nop 1
	v_cndmask_b32_e64 v19, 0, v23, s[0:1]
	v_add_u32_e32 v2, v19, v2
	v_cmp_lt_u32_e64 s[10:11], 31, v2
	s_nop 1
	v_cndmask_b32_e64 v19, 0, v24, s[10:11]
	v_add_u32_e32 v2, v19, v2
	v_cmp_lt_u32_e64 s[12:13], 31, v2
	s_nop 1
	v_cndmask_b32_e64 v19, 0, v24, s[12:13]
	v_add_u32_e32 v19, v19, v2
	v_and_b32_e32 v2, 0x7fffff, v18
	v_or_b32_e32 v44, 0x800000, v2
	v_mad_u64_u32 v[32:33], s[14:15], v44, s66, 0
	v_mov_b32_e32 v2, v33
	v_mad_u64_u32 v[34:35], s[14:15], v44, s67, v[2:3]
	v_mov_b32_e32 v2, v35
	v_mad_u64_u32 v[36:37], s[14:15], v44, s68, v[2:3]
	v_mov_b32_e32 v2, v37
	v_mad_u64_u32 v[38:39], s[14:15], v44, s69, v[2:3]
	v_mov_b32_e32 v2, v39
	v_mad_u64_u32 v[40:41], s[14:15], v44, s54, v[2:3]
	v_mov_b32_e32 v2, v41
	v_mad_u64_u32 v[42:43], s[14:15], v44, s78, v[2:3]
	v_mov_b32_e32 v2, v43
	v_mad_u64_u32 v[44:45], s[14:15], v44, s30, v[2:3]
	v_cndmask_b32_e64 v33, v42, v38, s[0:1]
	v_cndmask_b32_e64 v2, v44, v40, s[0:1]
	v_cndmask_b32_e64 v37, v45, v42, s[0:1]
	v_cndmask_b32_e64 v35, v2, v33, s[10:11]
	v_cndmask_b32_e64 v2, v37, v2, s[10:11]
	v_cndmask_b32_e64 v37, v40, v36, s[0:1]
	v_cndmask_b32_e64 v33, v33, v37, s[10:11]
	v_sub_u32_e32 v39, 32, v19
	v_cmp_eq_u32_e64 s[14:15], 0, v19
	v_cndmask_b32_e64 v19, v38, v34, s[0:1]
	v_cndmask_b32_e64 v2, v2, v35, s[12:13]
	v_cndmask_b32_e64 v35, v35, v33, s[12:13]
	v_cndmask_b32_e64 v34, v37, v19, s[10:11]
	v_alignbit_b32 v40, v2, v35, v39
	v_cndmask_b32_e64 v33, v33, v34, s[12:13]
	v_cndmask_b32_e64 v2, v40, v2, s[14:15]
	v_alignbit_b32 v37, v35, v33, v39
	v_cndmask_b32_e64 v32, v36, v32, s[0:1]
	v_cndmask_b32_e64 v35, v37, v35, s[14:15]
	v_bfe_u32 v40, v2, 29, 1
	v_cndmask_b32_e64 v19, v19, v32, s[10:11]
	v_alignbit_b32 v37, v2, v35, 30
	v_sub_u32_e32 v41, 0, v40
	v_cndmask_b32_e64 v19, v34, v19, s[12:13]
	v_xor_b32_e32 v37, v37, v41
	v_alignbit_b32 v32, v33, v19, v39
	v_cndmask_b32_e64 v32, v32, v33, s[14:15]
	v_ffbh_u32_e32 v34, v37
	v_alignbit_b32 v33, v35, v32, 30
	v_min_u32_e32 v34, 32, v34
	v_alignbit_b32 v19, v32, v19, 30
	v_xor_b32_e32 v33, v33, v41
	v_sub_u32_e32 v35, 31, v34
	v_xor_b32_e32 v19, v19, v41
	v_alignbit_b32 v36, v37, v33, v35
	v_alignbit_b32 v19, v33, v19, v35
	v_alignbit_b32 v32, v36, v19, 9
	v_ffbh_u32_e32 v33, v32
	v_min_u32_e32 v33, 32, v33
	v_lshrrev_b32_e32 v38, 29, v2
	v_not_b32_e32 v35, v33
	v_alignbit_b32 v19, v32, v19, v35
	v_lshlrev_b32_e32 v32, 31, v38
	v_or_b32_e32 v35, 0x33000000, v32
	v_add_lshl_u32 v33, v33, v34, 23
	v_lshrrev_b32_e32 v19, 9, v19
	v_sub_u32_e32 v33, v35, v33
	v_or_b32_e32 v32, 0.5, v32
	v_lshlrev_b32_e32 v34, 23, v34
	v_or_b32_e32 v19, v33, v19
	v_lshrrev_b32_e32 v33, 9, v36
	v_sub_u32_e32 v32, v32, v34
	v_or_b32_e32 v32, v33, v32
	v_mul_f32_e32 v33, 0x3fc90fda, v32
	v_fma_f32 v34, v32, s31, -v33
	v_fmac_f32_e32 v34, 0x33a22168, v32
	v_fmac_f32_e32 v34, 0x3fc90fda, v19
	v_lshrrev_b32_e32 v2, 30, v2
	v_add_f32_e32 v19, v33, v34
	v_add_u32_e32 v2, v40, v2

.LBB0_90:
	v_lshl_add_u64 v[18:19], v[14:15], 0, s[0:1]
	v_add_co_u32_e32 v18, vcc, 0x4000, v18
	s_add_u32 s0, s0, 0x400
	s_nop 0
	v_addc_co_u32_e32 v19, vcc, 0, v19, vcc
	global_load_dword v100, v[18:19], off
	global_load_dword v101, v[18:19], off offset:256
	global_load_dword v102, v[18:19], off offset:512
	global_load_dword v103, v[18:19], off offset:768
	s_addc_u32 s1, s1, 0
	v_lshl_add_u64 v[18:19], v[14:15], 0, s[0:1]
	v_add_co_u32_e32 v18, vcc, 0x4000, v18
	s_add_u32 s0, s0, 0x400
	s_nop 0
	v_addc_co_u32_e32 v19, vcc, 0, v19, vcc
	global_load_dword v104, v[18:19], off
	global_load_dword v105, v[18:19], off offset:256
	global_load_dword v106, v[18:19], off offset:512
	global_load_dword v107, v[18:19], off offset:768
	s_addc_u32 s1, s1, 0
	v_lshl_add_u64 v[18:19], v[14:15], 0, s[0:1]
	v_add_co_u32_e32 v18, vcc, 0x4000, v18
	s_add_u32 s0, s0, 0x400
	s_nop 0
	v_addc_co_u32_e32 v19, vcc, 0, v19, vcc
	global_load_dword v108, v[18:19], off
	global_load_dword v109, v[18:19], off offset:256
	global_load_dword v110, v[18:19], off offset:512
	global_load_dword v111, v[18:19], off offset:768
	s_addc_u32 s1, s1, 0
	v_lshl_add_u64 v[18:19], v[14:15], 0, s[0:1]
	v_add_co_u32_e32 v18, vcc, 0x4000, v18
	s_add_u32 s0, s0, 0x400
	s_nop 0
	v_addc_co_u32_e32 v19, vcc, 0, v19, vcc
	global_load_dword v112, v[18:19], off
	global_load_dword v113, v[18:19], off offset:256
	global_load_dword v114, v[18:19], off offset:512
	global_load_dword v115, v[18:19], off offset:768
	s_addc_u32 s1, s1, 0
	v_lshl_add_u64 v[18:19], v[14:15], 0, s[0:1]
	v_add_co_u32_e32 v18, vcc, 0x4000, v18
	s_add_u32 s0, s0, 0x400
	s_nop 0
	v_addc_co_u32_e32 v19, vcc, 0, v19, vcc
	global_load_dword v116, v[18:19], off
	global_load_dword v117, v[18:19], off offset:256
	global_load_dword v118, v[18:19], off offset:512
	global_load_dword v119, v[18:19], off offset:768
	s_addc_u32 s1, s1, 0
	v_lshl_add_u64 v[18:19], v[14:15], 0, s[0:1]
	v_add_co_u32_e32 v18, vcc, 0x4000, v18
	s_add_u32 s0, s0, 0x400
	s_nop 0
	v_addc_co_u32_e32 v19, vcc, 0, v19, vcc
	global_load_dword v120, v[18:19], off
	global_load_dword v121, v[18:19], off offset:256
	global_load_dword v122, v[18:19], off offset:512
	global_load_dword v123, v[18:19], off offset:768
	s_addc_u32 s1, s1, 0
	v_lshl_add_u64 v[18:19], v[14:15], 0, s[0:1]
	v_add_co_u32_e32 v18, vcc, 0x4000, v18
	s_add_u32 s0, s0, 0x400
	s_nop 0
	v_addc_co_u32_e32 v19, vcc, 0, v19, vcc
	global_load_dword v124, v[18:19], off
	global_load_dword v125, v[18:19], off offset:256
	global_load_dword v126, v[18:19], off offset:512
	global_load_dword v127, v[18:19], off offset:768
	s_addc_u32 s1, s1, 0
	v_lshl_add_u64 v[18:19], v[14:15], 0, s[0:1]
	v_add_co_u32_e32 v18, vcc, 0x4000, v18
	s_add_u32 s0, s0, 0x400
	s_nop 0
	v_addc_co_u32_e32 v19, vcc, 0, v19, vcc
	global_load_dword v128, v[18:19], off
	global_load_dword v129, v[18:19], off offset:256
	global_load_dword v130, v[18:19], off offset:512
	global_load_dword v131, v[18:19], off offset:768
	s_addc_u32 s1, s1, 0
	ds_read_b128 v[32:35], v31 offset:0
	ds_read_b128 v[164:167], v31 offset:16
	s_waitcnt vmcnt(31) lgkmcnt(1)
	v_fmac_f32_e32 v17, v32, v100
	s_waitcnt vmcnt(30)
	v_fmac_f32_e32 v17, v33, v101
	s_waitcnt vmcnt(29)
	v_fmac_f32_e32 v17, v34, v102
	s_waitcnt vmcnt(28)
	v_fmac_f32_e32 v17, v35, v103
	ds_read_b128 v[32:35], v31 offset:32
	s_waitcnt vmcnt(27) lgkmcnt(1)
	v_fmac_f32_e32 v17, v164, v104
	s_waitcnt vmcnt(26)
	v_fmac_f32_e32 v17, v165, v105
	s_waitcnt vmcnt(25)
	v_fmac_f32_e32 v17, v166, v106
	s_waitcnt vmcnt(24)
	v_fmac_f32_e32 v17, v167, v107
	ds_read_b128 v[164:167], v31 offset:48
	s_waitcnt vmcnt(23) lgkmcnt(1)
	v_fmac_f32_e32 v17, v32, v108
	s_waitcnt vmcnt(22)
	v_fmac_f32_e32 v17, v33, v109
	s_waitcnt vmcnt(21)
	v_fmac_f32_e32 v17, v34, v110
	s_waitcnt vmcnt(20)
	v_fmac_f32_e32 v17, v35, v111
	ds_read_b128 v[32:35], v31 offset:64
	s_waitcnt vmcnt(19) lgkmcnt(1)
	v_fmac_f32_e32 v17, v164, v112
	s_waitcnt vmcnt(18)
	v_fmac_f32_e32 v17, v165, v113
	s_waitcnt vmcnt(17)
	v_fmac_f32_e32 v17, v166, v114
	s_waitcnt vmcnt(16)
	v_fmac_f32_e32 v17, v167, v115
	ds_read_b128 v[164:167], v31 offset:80
	s_waitcnt vmcnt(15) lgkmcnt(1)
	v_fmac_f32_e32 v17, v32, v116
	s_waitcnt vmcnt(14)
	v_fmac_f32_e32 v17, v33, v117
	s_waitcnt vmcnt(13)
	v_fmac_f32_e32 v17, v34, v118
	s_waitcnt vmcnt(12)
	v_fmac_f32_e32 v17, v35, v119
	ds_read_b128 v[32:35], v31 offset:96
	s_waitcnt vmcnt(11) lgkmcnt(1)
	v_fmac_f32_e32 v17, v164, v120
	s_waitcnt vmcnt(10)
	v_fmac_f32_e32 v17, v165, v121
	s_waitcnt vmcnt(9)
	v_fmac_f32_e32 v17, v166, v122
	s_waitcnt vmcnt(8)
	v_fmac_f32_e32 v17, v167, v123
	ds_read_b128 v[164:167], v31 offset:112
	s_waitcnt vmcnt(7) lgkmcnt(1)
	v_fmac_f32_e32 v17, v32, v124
	s_waitcnt vmcnt(6)
	v_fmac_f32_e32 v17, v33, v125
	s_waitcnt vmcnt(5)
	v_fmac_f32_e32 v17, v34, v126
	s_waitcnt vmcnt(4)
	v_fmac_f32_e32 v17, v35, v127
	s_waitcnt vmcnt(3) lgkmcnt(0)
	v_fmac_f32_e32 v17, v164, v128
	s_waitcnt vmcnt(2)
	v_fmac_f32_e32 v17, v165, v129
	s_waitcnt vmcnt(1)
	v_fmac_f32_e32 v17, v166, v130
	s_waitcnt vmcnt(0)
	v_fmac_f32_e32 v17, v167, v131
	v_lshl_add_u64 v[18:19], v[14:15], 0, s[0:1]
	v_add_co_u32_e32 v18, vcc, 0x4000, v18
	s_add_u32 s0, s0, 0x400
	s_nop 0
	v_addc_co_u32_e32 v19, vcc, 0, v19, vcc
	global_load_dword v100, v[18:19], off
	global_load_dword v101, v[18:19], off offset:256
	global_load_dword v102, v[18:19], off offset:512
	global_load_dword v103, v[18:19], off offset:768
	s_addc_u32 s1, s1, 0
	v_lshl_add_u64 v[18:19], v[14:15], 0, s[0:1]
	v_add_co_u32_e32 v18, vcc, 0x4000, v18
	s_add_u32 s0, s0, 0x400
	s_nop 0
	v_addc_co_u32_e32 v19, vcc, 0, v19, vcc
	global_load_dword v104, v[18:19], off
	global_load_dword v105, v[18:19], off offset:256
	global_load_dword v106, v[18:19], off offset:512
	global_load_dword v107, v[18:19], off offset:768
	s_addc_u32 s1, s1, 0
	v_lshl_add_u64 v[18:19], v[14:15], 0, s[0:1]
	v_add_co_u32_e32 v18, vcc, 0x4000, v18
	s_add_u32 s0, s0, 0x400
	s_nop 0
	v_addc_co_u32_e32 v19, vcc, 0, v19, vcc
	global_load_dword v108, v[18:19], off
	global_load_dword v109, v[18:19], off offset:256
	global_load_dword v110, v[18:19], off offset:512
	global_load_dword v111, v[18:19], off offset:768
	s_addc_u32 s1, s1, 0
	v_lshl_add_u64 v[18:19], v[14:15], 0, s[0:1]
	v_add_co_u32_e32 v18, vcc, 0x4000, v18
	s_add_u32 s0, s0, 0x400
	s_nop 0
	v_addc_co_u32_e32 v19, vcc, 0, v19, vcc
	global_load_dword v112, v[18:19], off
	global_load_dword v113, v[18:19], off offset:256
	global_load_dword v114, v[18:19], off offset:512
	global_load_dword v115, v[18:19], off offset:768
	s_addc_u32 s1, s1, 0
	v_lshl_add_u64 v[18:19], v[14:15], 0, s[0:1]
	v_add_co_u32_e32 v18, vcc, 0x4000, v18
	s_add_u32 s0, s0, 0x400
	s_nop 0
	v_addc_co_u32_e32 v19, vcc, 0, v19, vcc
	global_load_dword v116, v[18:19], off
	global_load_dword v117, v[18:19], off offset:256
	global_load_dword v118, v[18:19], off offset:512
	global_load_dword v119, v[18:19], off offset:768
	s_addc_u32 s1, s1, 0
	v_lshl_add_u64 v[18:19], v[14:15], 0, s[0:1]
	v_add_co_u32_e32 v18, vcc, 0x4000, v18
	s_add_u32 s0, s0, 0x400
	s_nop 0
	v_addc_co_u32_e32 v19, vcc, 0, v19, vcc
	global_load_dword v120, v[18:19], off
	global_load_dword v121, v[18:19], off offset:256
	global_load_dword v122, v[18:19], off offset:512
	global_load_dword v123, v[18:19], off offset:768
	s_addc_u32 s1, s1, 0
	v_lshl_add_u64 v[18:19], v[14:15], 0, s[0:1]
	v_add_co_u32_e32 v18, vcc, 0x4000, v18
	s_add_u32 s0, s0, 0x400
	s_nop 0
	v_addc_co_u32_e32 v19, vcc, 0, v19, vcc
	global_load_dword v124, v[18:19], off
	global_load_dword v125, v[18:19], off offset:256
	global_load_dword v126, v[18:19], off offset:512
	global_load_dword v127, v[18:19], off offset:768
	s_addc_u32 s1, s1, 0
	v_lshl_add_u64 v[18:19], v[14:15], 0, s[0:1]
	v_add_co_u32_e32 v18, vcc, 0x4000, v18
	s_add_u32 s0, s0, 0x400
	s_nop 0
	v_addc_co_u32_e32 v19, vcc, 0, v19, vcc
	global_load_dword v128, v[18:19], off
	global_load_dword v129, v[18:19], off offset:256
	global_load_dword v130, v[18:19], off offset:512
	global_load_dword v131, v[18:19], off offset:768
	s_addc_u32 s1, s1, 0
	ds_read_b128 v[32:35], v31 offset:128
	ds_read_b128 v[164:167], v31 offset:144
	s_waitcnt vmcnt(31) lgkmcnt(1)
	v_fmac_f32_e32 v17, v32, v100
	s_waitcnt vmcnt(30)
	v_fmac_f32_e32 v17, v33, v101
	s_waitcnt vmcnt(29)
	v_fmac_f32_e32 v17, v34, v102
	s_waitcnt vmcnt(28)
	v_fmac_f32_e32 v17, v35, v103
	ds_read_b128 v[32:35], v31 offset:160
	s_waitcnt vmcnt(27) lgkmcnt(1)
	v_fmac_f32_e32 v17, v164, v104
	s_waitcnt vmcnt(26)
	v_fmac_f32_e32 v17, v165, v105
	s_waitcnt vmcnt(25)
	v_fmac_f32_e32 v17, v166, v106
	s_waitcnt vmcnt(24)
	v_fmac_f32_e32 v17, v167, v107
	ds_read_b128 v[164:167], v31 offset:176
	s_waitcnt vmcnt(23) lgkmcnt(1)
	v_fmac_f32_e32 v17, v32, v108
	s_waitcnt vmcnt(22)
	v_fmac_f32_e32 v17, v33, v109
	s_waitcnt vmcnt(21)
	v_fmac_f32_e32 v17, v34, v110
	s_waitcnt vmcnt(20)
	v_fmac_f32_e32 v17, v35, v111
	ds_read_b128 v[32:35], v31 offset:192
	s_waitcnt vmcnt(19) lgkmcnt(1)
	v_fmac_f32_e32 v17, v164, v112
	s_waitcnt vmcnt(18)
	v_fmac_f32_e32 v17, v165, v113
	s_waitcnt vmcnt(17)
	v_fmac_f32_e32 v17, v166, v114
	s_waitcnt vmcnt(16)
	v_fmac_f32_e32 v17, v167, v115
	ds_read_b128 v[164:167], v31 offset:208
	s_waitcnt vmcnt(15) lgkmcnt(1)
	v_fmac_f32_e32 v17, v32, v116
	s_waitcnt vmcnt(14)
	v_fmac_f32_e32 v17, v33, v117
	s_waitcnt vmcnt(13)
	v_fmac_f32_e32 v17, v34, v118
	s_waitcnt vmcnt(12)
	v_fmac_f32_e32 v17, v35, v119
	ds_read_b128 v[32:35], v31 offset:224
	s_waitcnt vmcnt(11) lgkmcnt(1)
	v_fmac_f32_e32 v17, v164, v120
	s_waitcnt vmcnt(10)
	v_fmac_f32_e32 v17, v165, v121
	s_waitcnt vmcnt(9)
	v_fmac_f32_e32 v17, v166, v122
	s_waitcnt vmcnt(8)
	v_fmac_f32_e32 v17, v167, v123
	ds_read_b128 v[164:167], v31 offset:240
	s_waitcnt vmcnt(7) lgkmcnt(1)
	v_fmac_f32_e32 v17, v32, v124
	s_waitcnt vmcnt(6)
	v_fmac_f32_e32 v17, v33, v125
	s_waitcnt vmcnt(5)
	v_fmac_f32_e32 v17, v34, v126
	s_waitcnt vmcnt(4)
	v_fmac_f32_e32 v17, v35, v127
	s_waitcnt vmcnt(3) lgkmcnt(0)
	v_fmac_f32_e32 v17, v164, v128
	s_waitcnt vmcnt(2)
	v_fmac_f32_e32 v17, v165, v129
	s_waitcnt vmcnt(1)
	v_fmac_f32_e32 v17, v166, v130
	s_waitcnt vmcnt(0)
	v_fmac_f32_e32 v17, v167, v131
	v_add_u32_e32 v2, 0x100, v2
	v_and_b32_e32 v18, 0x7fffffff, v17
	v_cmp_nlt_f32_e64 s[0:1], |v17|, s65
	s_and_saveexec_b64 s[10:11], s[0:1]
	s_xor_b64 s[16:17], exec, s[10:11]
	s_cbranch_execz .LBB0_93
	v_lshrrev_b32_e32 v2, 23, v18
	v_add_u32_e32 v2, 0xffffff88, v2
	v_cmp_lt_u32_e32 vcc, 63, v2
	s_nop 1
	v_cndmask_b32_e32 v19, 0, v23, vcc
	v_add_u32_e32 v2, v19, v2
	v_cmp_lt_u32_e64 s[0:1], 31, v2
	s_nop 1
	v_cndmask_b32_e64 v19, 0, v24, s[0:1]
	v_add_u32_e32 v2, v19, v2
	v_cmp_lt_u32_e64 s[10:11], 31, v2
	s_nop 1
	v_cndmask_b32_e64 v19, 0, v24, s[10:11]
	v_add_u32_e32 v19, v19, v2
	v_and_b32_e32 v2, 0x7fffff, v18
	v_or_b32_e32 v44, 0x800000, v2
	v_mad_u64_u32 v[32:33], s[12:13], v44, s66, 0
	v_mov_b32_e32 v2, v33
	v_mad_u64_u32 v[34:35], s[12:13], v44, s67, v[2:3]
	v_mov_b32_e32 v2, v35
	v_mad_u64_u32 v[36:37], s[12:13], v44, s68, v[2:3]
	v_mov_b32_e32 v2, v37
	v_mad_u64_u32 v[38:39], s[12:13], v44, s69, v[2:3]
	v_mov_b32_e32 v2, v39
	v_mad_u64_u32 v[40:41], s[12:13], v44, s54, v[2:3]
	v_mov_b32_e32 v2, v41
	v_mad_u64_u32 v[42:43], s[12:13], v44, s78, v[2:3]
	v_mov_b32_e32 v2, v43
	v_mad_u64_u32 v[44:45], s[12:13], v44, s30, v[2:3]
	v_cndmask_b32_e32 v33, v42, v38, vcc
	v_cndmask_b32_e32 v2, v44, v40, vcc
	v_cndmask_b32_e32 v37, v45, v42, vcc
	v_cndmask_b32_e64 v35, v2, v33, s[0:1]
	v_cndmask_b32_e64 v2, v37, v2, s[0:1]
	v_cndmask_b32_e32 v37, v40, v36, vcc
	v_cndmask_b32_e64 v33, v33, v37, s[0:1]
	v_sub_u32_e32 v39, 32, v19
	v_cmp_eq_u32_e64 s[12:13], 0, v19
	v_cndmask_b32_e32 v19, v38, v34, vcc
	v_cndmask_b32_e64 v2, v2, v35, s[10:11]
	v_cndmask_b32_e64 v35, v35, v33, s[10:11]
	v_cndmask_b32_e64 v34, v37, v19, s[0:1]
	v_alignbit_b32 v40, v2, v35, v39
	v_cndmask_b32_e64 v33, v33, v34, s[10:11]
	v_cndmask_b32_e64 v2, v40, v2, s[12:13]
	v_alignbit_b32 v37, v35, v33, v39
	v_cndmask_b32_e32 v32, v36, v32, vcc
	v_cndmask_b32_e64 v35, v37, v35, s[12:13]
	v_bfe_u32 v40, v2, 29, 1
	v_cndmask_b32_e64 v19, v19, v32, s[0:1]
	v_alignbit_b32 v37, v2, v35, 30
	v_sub_u32_e32 v41, 0, v40
	v_cndmask_b32_e64 v19, v34, v19, s[10:11]
	v_xor_b32_e32 v37, v37, v41
	v_alignbit_b32 v32, v33, v19, v39
	v_cndmask_b32_e64 v32, v32, v33, s[12:13]
	v_ffbh_u32_e32 v34, v37
	v_alignbit_b32 v33, v35, v32, 30
	v_min_u32_e32 v34, 32, v34
	v_alignbit_b32 v19, v32, v19, 30
	v_xor_b32_e32 v33, v33, v41
	v_sub_u32_e32 v35, 31, v34
	v_xor_b32_e32 v19, v19, v41
	v_alignbit_b32 v36, v37, v33, v35
	v_alignbit_b32 v19, v33, v19, v35
	v_alignbit_b32 v32, v36, v19, 9
	v_ffbh_u32_e32 v33, v32
	v_min_u32_e32 v33, 32, v33
	v_lshrrev_b32_e32 v38, 29, v2
	v_not_b32_e32 v35, v33
	v_alignbit_b32 v19, v32, v19, v35
	v_lshlrev_b32_e32 v32, 31, v38
	v_or_b32_e32 v35, 0x33000000, v32
	v_add_lshl_u32 v33, v33, v34, 23
	v_lshrrev_b32_e32 v19, 9, v19
	v_sub_u32_e32 v33, v35, v33
	v_or_b32_e32 v32, 0.5, v32
	v_lshlrev_b32_e32 v34, 23, v34
	v_or_b32_e32 v19, v33, v19
	v_lshrrev_b32_e32 v33, 9, v36
	v_sub_u32_e32 v32, v32, v34
	v_or_b32_e32 v32, v33, v32
	v_mul_f32_e32 v33, 0x3fc90fda, v32
	v_fma_f32 v34, v32, s31, -v33
	v_fmac_f32_e32 v34, 0x33a22168, v32
	v_fmac_f32_e32 v34, 0x3fc90fda, v19
	v_lshrrev_b32_e32 v2, 30, v2
	v_add_f32_e32 v19, v33, v34
	v_add_u32_e32 v2, v40, v2

.LBB0_116:
	global_load_dword v100, v[18:19], off offset:-256
	global_load_dword v101, v[18:19], off
	global_load_dword v102, v[18:19], off offset:256
	v_lshl_add_u64 v[18:19], v[18:19], 0, s[70:71]
	global_load_dword v103, v[18:19], off offset:-256
	global_load_dword v104, v[18:19], off
	global_load_dword v105, v[18:19], off offset:256
	v_lshl_add_u64 v[18:19], v[18:19], 0, s[70:71]
	global_load_dword v106, v[18:19], off offset:-256
	global_load_dword v107, v[18:19], off
	global_load_dword v108, v[18:19], off offset:256
	v_lshl_add_u64 v[18:19], v[18:19], 0, s[70:71]
	global_load_dword v109, v[18:19], off offset:-256
	global_load_dword v110, v[18:19], off
	global_load_dword v111, v[18:19], off offset:256
	v_lshl_add_u64 v[18:19], v[18:19], 0, s[70:71]
	global_load_dword v112, v[18:19], off offset:-256
	global_load_dword v113, v[18:19], off
	global_load_dword v114, v[18:19], off offset:256
	v_lshl_add_u64 v[18:19], v[18:19], 0, s[70:71]
	global_load_dword v115, v[18:19], off offset:-256
	global_load_dword v116, v[18:19], off
	global_load_dword v117, v[18:19], off offset:256
	v_lshl_add_u64 v[18:19], v[18:19], 0, s[70:71]
	global_load_dword v118, v[18:19], off offset:-256
	global_load_dword v119, v[18:19], off
	global_load_dword v120, v[18:19], off offset:256
	v_lshl_add_u64 v[18:19], v[18:19], 0, s[70:71]
	global_load_dword v121, v[18:19], off offset:-256
	global_load_dword v122, v[18:19], off
	global_load_dword v123, v[18:19], off offset:256
	v_lshl_add_u64 v[18:19], v[18:19], 0, s[70:71]
	global_load_dword v124, v[18:19], off offset:-256
	global_load_dword v125, v[18:19], off
	global_load_dword v126, v[18:19], off offset:256
	v_lshl_add_u64 v[18:19], v[18:19], 0, s[70:71]
	global_load_dword v127, v[18:19], off offset:-256
	global_load_dword v128, v[18:19], off
	global_load_dword v129, v[18:19], off offset:256
	v_lshl_add_u64 v[18:19], v[18:19], 0, s[70:71]
	global_load_dword v130, v[18:19], off offset:-256
	global_load_dword v131, v[18:19], off
	global_load_dword v132, v[18:19], off offset:256
	v_lshl_add_u64 v[18:19], v[18:19], 0, s[70:71]
	ds_read2_b32 v[32:33], v26 offset0:0 offset1:1
	ds_read_b32 v36, v26 offset:8
	ds_read2_b32 v[164:165], v26 offset0:3 offset1:4
	ds_read_b32 v166, v26 offset:20
	s_waitcnt vmcnt(32) lgkmcnt(3)
	v_fmac_f32_e32 v17, v32, v100
	s_waitcnt vmcnt(31)
	v_fmac_f32_e32 v17, v33, v101
	s_waitcnt vmcnt(30) lgkmcnt(2)
	v_fmac_f32_e32 v17, v36, v102
	ds_read2_b32 v[32:33], v26 offset0:6 offset1:7
	ds_read_b32 v36, v26 offset:32
	s_waitcnt vmcnt(29) lgkmcnt(3)
	v_fmac_f32_e32 v17, v164, v103
	s_waitcnt vmcnt(28)
	v_fmac_f32_e32 v17, v165, v104
	s_waitcnt vmcnt(27) lgkmcnt(2)
	v_fmac_f32_e32 v17, v166, v105
	ds_read2_b32 v[164:165], v26 offset0:9 offset1:10
	ds_read_b32 v166, v26 offset:44
	s_waitcnt vmcnt(26) lgkmcnt(3)
	v_fmac_f32_e32 v17, v32, v106
	s_waitcnt vmcnt(25)
	v_fmac_f32_e32 v17, v33, v107
	s_waitcnt vmcnt(24) lgkmcnt(2)
	v_fmac_f32_e32 v17, v36, v108
	ds_read2_b32 v[32:33], v26 offset0:12 offset1:13
	ds_read_b32 v36, v26 offset:56
	s_waitcnt vmcnt(23) lgkmcnt(3)
	v_fmac_f32_e32 v17, v164, v109
	s_waitcnt vmcnt(22)
	v_fmac_f32_e32 v17, v165, v110
	s_waitcnt vmcnt(21) lgkmcnt(2)
	v_fmac_f32_e32 v17, v166, v111
	ds_read2_b32 v[164:165], v26 offset0:15 offset1:16
	ds_read_b32 v166, v26 offset:68
	s_waitcnt vmcnt(20) lgkmcnt(3)
	v_fmac_f32_e32 v17, v32, v112
	s_waitcnt vmcnt(19)
	v_fmac_f32_e32 v17, v33, v113
	s_waitcnt vmcnt(18) lgkmcnt(2)
	v_fmac_f32_e32 v17, v36, v114
	ds_read2_b32 v[32:33], v26 offset0:18 offset1:19
	ds_read_b32 v36, v26 offset:80
	s_waitcnt vmcnt(17) lgkmcnt(3)
	v_fmac_f32_e32 v17, v164, v115
	s_waitcnt vmcnt(16)
	v_fmac_f32_e32 v17, v165, v116
	s_waitcnt vmcnt(15) lgkmcnt(2)
	v_fmac_f32_e32 v17, v166, v117
	ds_read2_b32 v[164:165], v26 offset0:21 offset1:22
	ds_read_b32 v166, v26 offset:92
	s_waitcnt vmcnt(14) lgkmcnt(3)
	v_fmac_f32_e32 v17, v32, v118
	s_waitcnt vmcnt(13)
	v_fmac_f32_e32 v17, v33, v119
	s_waitcnt vmcnt(12) lgkmcnt(2)
	v_fmac_f32_e32 v17, v36, v120
	ds_read2_b32 v[32:33], v26 offset0:24 offset1:25
	ds_read_b32 v36, v26 offset:104
	s_waitcnt vmcnt(11) lgkmcnt(3)
	v_fmac_f32_e32 v17, v164, v121
	s_waitcnt vmcnt(10)
	v_fmac_f32_e32 v17, v165, v122
	s_waitcnt vmcnt(9) lgkmcnt(2)
	v_fmac_f32_e32 v17, v166, v123
	ds_read2_b32 v[164:165], v26 offset0:27 offset1:28
	ds_read_b32 v166, v26 offset:116
	s_waitcnt vmcnt(8) lgkmcnt(3)
	v_fmac_f32_e32 v17, v32, v124
	s_waitcnt vmcnt(7)
	v_fmac_f32_e32 v17, v33, v125
	s_waitcnt vmcnt(6) lgkmcnt(2)
	v_fmac_f32_e32 v17, v36, v126
	ds_read2_b32 v[32:33], v26 offset0:30 offset1:31
	ds_read_b32 v36, v26 offset:128
	s_waitcnt vmcnt(5) lgkmcnt(3)
	v_fmac_f32_e32 v17, v164, v127
	s_waitcnt vmcnt(4)
	v_fmac_f32_e32 v17, v165, v128
	s_waitcnt vmcnt(3) lgkmcnt(2)
	v_fmac_f32_e32 v17, v166, v129
	s_waitcnt vmcnt(2) lgkmcnt(1)
	v_fmac_f32_e32 v17, v32, v130
	s_waitcnt vmcnt(1)
	v_fmac_f32_e32 v17, v33, v131
	s_waitcnt vmcnt(0) lgkmcnt(0)
	v_fmac_f32_e32 v17, v36, v132
	s_movk_i32 s0, 0x84
	v_and_b32_e32 v18, 0x7fffffff, v17
	v_cmp_nlt_f32_e64 s[0:1], |v17|, s65
	s_and_saveexec_b64 s[10:11], s[0:1]
	s_xor_b64 s[82:83], exec, s[10:11]
	s_cbranch_execz .LBB0_119
	v_lshrrev_b32_e32 v2, 23, v18
	v_add_u32_e32 v2, 0xffffff88, v2
	v_cmp_lt_u32_e64 s[0:1], 63, v2
	s_nop 1
	v_cndmask_b32_e64 v19, 0, v23, s[0:1]
	v_add_u32_e32 v2, v19, v2
	v_cmp_lt_u32_e64 s[10:11], 31, v2
	s_nop 1
	v_cndmask_b32_e64 v19, 0, v24, s[10:11]
	v_add_u32_e32 v2, v19, v2
	v_cmp_lt_u32_e64 s[12:13], 31, v2
	s_nop 1
	v_cndmask_b32_e64 v19, 0, v24, s[12:13]
	v_add_u32_e32 v19, v19, v2
	v_and_b32_e32 v2, 0x7fffff, v18
	v_or_b32_e32 v44, 0x800000, v2
	v_mad_u64_u32 v[32:33], s[14:15], v44, s66, 0
	v_mov_b32_e32 v2, v33
	v_mad_u64_u32 v[34:35], s[14:15], v44, s67, v[2:3]
	v_mov_b32_e32 v2, v35
	v_mad_u64_u32 v[36:37], s[14:15], v44, s68, v[2:3]
	v_mov_b32_e32 v2, v37
	v_mad_u64_u32 v[38:39], s[14:15], v44, s69, v[2:3]
	v_mov_b32_e32 v2, v39
	v_mad_u64_u32 v[40:41], s[14:15], v44, s54, v[2:3]
	v_mov_b32_e32 v2, v41
	v_mad_u64_u32 v[42:43], s[14:15], v44, s78, v[2:3]
	v_mov_b32_e32 v2, v43
	v_mad_u64_u32 v[44:45], s[14:15], v44, s30, v[2:3]
	v_cndmask_b32_e64 v33, v42, v38, s[0:1]
	v_cndmask_b32_e64 v2, v44, v40, s[0:1]
	v_cndmask_b32_e64 v37, v45, v42, s[0:1]
	v_cndmask_b32_e64 v35, v2, v33, s[10:11]
	v_cndmask_b32_e64 v2, v37, v2, s[10:11]
	v_cndmask_b32_e64 v37, v40, v36, s[0:1]
	v_cndmask_b32_e64 v33, v33, v37, s[10:11]
	v_sub_u32_e32 v39, 32, v19
	v_cmp_eq_u32_e64 s[14:15], 0, v19
	v_cndmask_b32_e64 v19, v38, v34, s[0:1]
	v_cndmask_b32_e64 v2, v2, v35, s[12:13]
	v_cndmask_b32_e64 v35, v35, v33, s[12:13]
	v_cndmask_b32_e64 v34, v37, v19, s[10:11]
	v_alignbit_b32 v40, v2, v35, v39
	v_cndmask_b32_e64 v33, v33, v34, s[12:13]
	v_cndmask_b32_e64 v2, v40, v2, s[14:15]
	v_alignbit_b32 v37, v35, v33, v39
	v_cndmask_b32_e64 v32, v36, v32, s[0:1]
	v_cndmask_b32_e64 v35, v37, v35, s[14:15]
	v_bfe_u32 v40, v2, 29, 1
	v_cndmask_b32_e64 v19, v19, v32, s[10:11]
	v_alignbit_b32 v37, v2, v35, 30
	v_sub_u32_e32 v41, 0, v40
	v_cndmask_b32_e64 v19, v34, v19, s[12:13]
	v_xor_b32_e32 v37, v37, v41
	v_alignbit_b32 v32, v33, v19, v39
	v_cndmask_b32_e64 v32, v32, v33, s[14:15]
	v_ffbh_u32_e32 v34, v37
	v_alignbit_b32 v33, v35, v32, 30
	v_min_u32_e32 v34, 32, v34
	v_alignbit_b32 v19, v32, v19, 30
	v_xor_b32_e32 v33, v33, v41
	v_sub_u32_e32 v35, 31, v34
	v_xor_b32_e32 v19, v19, v41
	v_alignbit_b32 v36, v37, v33, v35
	v_alignbit_b32 v19, v33, v19, v35
	v_alignbit_b32 v32, v36, v19, 9
	v_ffbh_u32_e32 v33, v32
	v_min_u32_e32 v33, 32, v33
	v_lshrrev_b32_e32 v38, 29, v2
	v_not_b32_e32 v35, v33
	v_alignbit_b32 v19, v32, v19, v35
	v_lshlrev_b32_e32 v32, 31, v38
	v_or_b32_e32 v35, 0x33000000, v32
	v_add_lshl_u32 v33, v33, v34, 23
	v_lshrrev_b32_e32 v19, 9, v19
	v_sub_u32_e32 v33, v35, v33
	v_or_b32_e32 v32, 0.5, v32
	v_lshlrev_b32_e32 v34, 23, v34
	v_or_b32_e32 v19, v33, v19
	v_lshrrev_b32_e32 v33, 9, v36
	v_sub_u32_e32 v32, v32, v34
	v_or_b32_e32 v32, v33, v32
	v_mul_f32_e32 v33, 0x3fc90fda, v32
	v_fma_f32 v34, v32, s31, -v33
	v_fmac_f32_e32 v34, 0x33a22168, v32
	v_fmac_f32_e32 v34, 0x3fc90fda, v19
	v_lshrrev_b32_e32 v2, 30, v2
	v_add_f32_e32 v19, v33, v34
	v_add_u32_e32 v2, v40, v2

.LBB0_124:
	global_load_dword v100, v[18:19], off offset:-512
	global_load_dword v101, v[18:19], off offset:-256
	global_load_dword v102, v[18:19], off
	global_load_dword v103, v[18:19], off offset:256
	v_lshl_add_u64 v[18:19], v[18:19], 0, s[80:81]
	global_load_dword v104, v[18:19], off offset:-512
	global_load_dword v105, v[18:19], off offset:-256
	global_load_dword v106, v[18:19], off
	global_load_dword v107, v[18:19], off offset:256
	v_lshl_add_u64 v[18:19], v[18:19], 0, s[80:81]
	global_load_dword v108, v[18:19], off offset:-512
	global_load_dword v109, v[18:19], off offset:-256
	global_load_dword v110, v[18:19], off
	global_load_dword v111, v[18:19], off offset:256
	v_lshl_add_u64 v[18:19], v[18:19], 0, s[80:81]
	global_load_dword v112, v[18:19], off offset:-512
	global_load_dword v113, v[18:19], off offset:-256
	global_load_dword v114, v[18:19], off
	global_load_dword v115, v[18:19], off offset:256
	v_lshl_add_u64 v[18:19], v[18:19], 0, s[80:81]
	global_load_dword v116, v[18:19], off offset:-512
	global_load_dword v117, v[18:19], off offset:-256
	global_load_dword v118, v[18:19], off
	global_load_dword v119, v[18:19], off offset:256
	v_lshl_add_u64 v[18:19], v[18:19], 0, s[80:81]
	global_load_dword v120, v[18:19], off offset:-512
	global_load_dword v121, v[18:19], off offset:-256
	global_load_dword v122, v[18:19], off
	global_load_dword v123, v[18:19], off offset:256
	v_lshl_add_u64 v[18:19], v[18:19], 0, s[80:81]
	global_load_dword v124, v[18:19], off offset:-512
	global_load_dword v125, v[18:19], off offset:-256
	global_load_dword v126, v[18:19], off
	global_load_dword v127, v[18:19], off offset:256
	v_lshl_add_u64 v[18:19], v[18:19], 0, s[80:81]
	global_load_dword v128, v[18:19], off offset:-512
	global_load_dword v129, v[18:19], off offset:-256
	global_load_dword v130, v[18:19], off
	global_load_dword v131, v[18:19], off offset:256
	v_lshl_add_u64 v[18:19], v[18:19], 0, s[80:81]
	ds_read_b128 v[32:35], v30 offset:0
	ds_read_b128 v[164:167], v30 offset:16
	s_waitcnt vmcnt(31) lgkmcnt(1)
	v_fmac_f32_e32 v17, v32, v100
	s_waitcnt vmcnt(30)
	v_fmac_f32_e32 v17, v33, v101
	s_waitcnt vmcnt(29)
	v_fmac_f32_e32 v17, v34, v102
	s_waitcnt vmcnt(28)
	v_fmac_f32_e32 v17, v35, v103
	ds_read_b128 v[32:35], v30 offset:32
	s_waitcnt vmcnt(27) lgkmcnt(1)
	v_fmac_f32_e32 v17, v164, v104
	s_waitcnt vmcnt(26)
	v_fmac_f32_e32 v17, v165, v105
	s_waitcnt vmcnt(25)
	v_fmac_f32_e32 v17, v166, v106
	s_waitcnt vmcnt(24)
	v_fmac_f32_e32 v17, v167, v107
	ds_read_b128 v[164:167], v30 offset:48
	s_waitcnt vmcnt(23) lgkmcnt(1)
	v_fmac_f32_e32 v17, v32, v108
	s_waitcnt vmcnt(22)
	v_fmac_f32_e32 v17, v33, v109
	s_waitcnt vmcnt(21)
	v_fmac_f32_e32 v17, v34, v110
	s_waitcnt vmcnt(20)
	v_fmac_f32_e32 v17, v35, v111
	ds_read_b128 v[32:35], v30 offset:64
	s_waitcnt vmcnt(19) lgkmcnt(1)
	v_fmac_f32_e32 v17, v164, v112
	s_waitcnt vmcnt(18)
	v_fmac_f32_e32 v17, v165, v113
	s_waitcnt vmcnt(17)
	v_fmac_f32_e32 v17, v166, v114
	s_waitcnt vmcnt(16)
	v_fmac_f32_e32 v17, v167, v115
	ds_read_b128 v[164:167], v30 offset:80
	s_waitcnt vmcnt(15) lgkmcnt(1)
	v_fmac_f32_e32 v17, v32, v116
	s_waitcnt vmcnt(14)
	v_fmac_f32_e32 v17, v33, v117
	s_waitcnt vmcnt(13)
	v_fmac_f32_e32 v17, v34, v118
	s_waitcnt vmcnt(12)
	v_fmac_f32_e32 v17, v35, v119
	ds_read_b128 v[32:35], v30 offset:96
	s_waitcnt vmcnt(11) lgkmcnt(1)
	v_fmac_f32_e32 v17, v164, v120
	s_waitcnt vmcnt(10)
	v_fmac_f32_e32 v17, v165, v121
	s_waitcnt vmcnt(9)
	v_fmac_f32_e32 v17, v166, v122
	s_waitcnt vmcnt(8)
	v_fmac_f32_e32 v17, v167, v123
	ds_read_b128 v[164:167], v30 offset:112
	s_waitcnt vmcnt(7) lgkmcnt(1)
	v_fmac_f32_e32 v17, v32, v124
	s_waitcnt vmcnt(6)
	v_fmac_f32_e32 v17, v33, v125
	s_waitcnt vmcnt(5)
	v_fmac_f32_e32 v17, v34, v126
	s_waitcnt vmcnt(4)
	v_fmac_f32_e32 v17, v35, v127
	s_waitcnt vmcnt(3) lgkmcnt(0)
	v_fmac_f32_e32 v17, v164, v128
	s_waitcnt vmcnt(2)
	v_fmac_f32_e32 v17, v165, v129
	s_waitcnt vmcnt(1)
	v_fmac_f32_e32 v17, v166, v130
	s_waitcnt vmcnt(0)
	v_fmac_f32_e32 v17, v167, v131
	global_load_dword v100, v[18:19], off offset:-512
	global_load_dword v101, v[18:19], off offset:-256
	global_load_dword v102, v[18:19], off
	global_load_dword v103, v[18:19], off offset:256
	v_lshl_add_u64 v[18:19], v[18:19], 0, s[80:81]
	global_load_dword v104, v[18:19], off offset:-512
	global_load_dword v105, v[18:19], off offset:-256
	global_load_dword v106, v[18:19], off
	global_load_dword v107, v[18:19], off offset:256
	v_lshl_add_u64 v[18:19], v[18:19], 0, s[80:81]
	global_load_dword v108, v[18:19], off offset:-512
	global_load_dword v109, v[18:19], off offset:-256
	global_load_dword v110, v[18:19], off
	global_load_dword v111, v[18:19], off offset:256
	v_lshl_add_u64 v[18:19], v[18:19], 0, s[80:81]
	global_load_dword v112, v[18:19], off offset:-512
	global_load_dword v113, v[18:19], off offset:-256
	global_load_dword v114, v[18:19], off
	global_load_dword v115, v[18:19], off offset:256
	v_lshl_add_u64 v[18:19], v[18:19], 0, s[80:81]
	global_load_dword v116, v[18:19], off offset:-512
	global_load_dword v117, v[18:19], off offset:-256
	global_load_dword v118, v[18:19], off
	global_load_dword v119, v[18:19], off offset:256
	v_lshl_add_u64 v[18:19], v[18:19], 0, s[80:81]
	global_load_dword v120, v[18:19], off offset:-512
	global_load_dword v121, v[18:19], off offset:-256
	global_load_dword v122, v[18:19], off
	global_load_dword v123, v[18:19], off offset:256
	v_lshl_add_u64 v[18:19], v[18:19], 0, s[80:81]
	global_load_dword v124, v[18:19], off offset:-512
	global_load_dword v125, v[18:19], off offset:-256
	global_load_dword v126, v[18:19], off
	global_load_dword v127, v[18:19], off offset:256
	v_lshl_add_u64 v[18:19], v[18:19], 0, s[80:81]
	global_load_dword v128, v[18:19], off offset:-512
	global_load_dword v129, v[18:19], off offset:-256
	global_load_dword v130, v[18:19], off
	global_load_dword v131, v[18:19], off offset:256
	v_lshl_add_u64 v[18:19], v[18:19], 0, s[80:81]
	ds_read_b128 v[32:35], v30 offset:128
	ds_read_b128 v[164:167], v30 offset:144
	s_waitcnt vmcnt(31) lgkmcnt(1)
	v_fmac_f32_e32 v17, v32, v100
	s_waitcnt vmcnt(30)
	v_fmac_f32_e32 v17, v33, v101
	s_waitcnt vmcnt(29)
	v_fmac_f32_e32 v17, v34, v102
	s_waitcnt vmcnt(28)
	v_fmac_f32_e32 v17, v35, v103
	ds_read_b128 v[32:35], v30 offset:160
	s_waitcnt vmcnt(27) lgkmcnt(1)
	v_fmac_f32_e32 v17, v164, v104
	s_waitcnt vmcnt(26)
	v_fmac_f32_e32 v17, v165, v105
	s_waitcnt vmcnt(25)
	v_fmac_f32_e32 v17, v166, v106
	s_waitcnt vmcnt(24)
	v_fmac_f32_e32 v17, v167, v107
	ds_read_b128 v[164:167], v30 offset:176
	s_waitcnt vmcnt(23) lgkmcnt(1)
	v_fmac_f32_e32 v17, v32, v108
	s_waitcnt vmcnt(22)
	v_fmac_f32_e32 v17, v33, v109
	s_waitcnt vmcnt(21)
	v_fmac_f32_e32 v17, v34, v110
	s_waitcnt vmcnt(20)
	v_fmac_f32_e32 v17, v35, v111
	ds_read_b128 v[32:35], v30 offset:192
	s_waitcnt vmcnt(19) lgkmcnt(1)
	v_fmac_f32_e32 v17, v164, v112
	s_waitcnt vmcnt(18)
	v_fmac_f32_e32 v17, v165, v113
	s_waitcnt vmcnt(17)
	v_fmac_f32_e32 v17, v166, v114
	s_waitcnt vmcnt(16)
	v_fmac_f32_e32 v17, v167, v115
	ds_read_b128 v[164:167], v30 offset:208
	s_waitcnt vmcnt(15) lgkmcnt(1)
	v_fmac_f32_e32 v17, v32, v116
	s_waitcnt vmcnt(14)
	v_fmac_f32_e32 v17, v33, v117
	s_waitcnt vmcnt(13)
	v_fmac_f32_e32 v17, v34, v118
	s_waitcnt vmcnt(12)
	v_fmac_f32_e32 v17, v35, v119
	ds_read_b128 v[32:35], v30 offset:224
	s_waitcnt vmcnt(11) lgkmcnt(1)
	v_fmac_f32_e32 v17, v164, v120
	s_waitcnt vmcnt(10)
	v_fmac_f32_e32 v17, v165, v121
	s_waitcnt vmcnt(9)
	v_fmac_f32_e32 v17, v166, v122
	s_waitcnt vmcnt(8)
	v_fmac_f32_e32 v17, v167, v123
	ds_read_b128 v[164:167], v30 offset:240
	s_waitcnt vmcnt(7) lgkmcnt(1)
	v_fmac_f32_e32 v17, v32, v124
	s_waitcnt vmcnt(6)
	v_fmac_f32_e32 v17, v33, v125
	s_waitcnt vmcnt(5)
	v_fmac_f32_e32 v17, v34, v126
	s_waitcnt vmcnt(4)
	v_fmac_f32_e32 v17, v35, v127
	s_waitcnt vmcnt(3) lgkmcnt(0)
	v_fmac_f32_e32 v17, v164, v128
	s_waitcnt vmcnt(2)
	v_fmac_f32_e32 v17, v165, v129
	s_waitcnt vmcnt(1)
	v_fmac_f32_e32 v17, v166, v130
	s_waitcnt vmcnt(0)
	v_fmac_f32_e32 v17, v167, v131
	s_movk_i32 s0, 0x100
	v_and_b32_e32 v18, 0x7fffffff, v17
	v_cmp_nlt_f32_e64 s[0:1], |v17|, s65
	s_and_saveexec_b64 s[10:11], s[0:1]
	s_xor_b64 s[82:83], exec, s[10:11]
	s_cbranch_execz .LBB0_127
	v_lshrrev_b32_e32 v2, 23, v18
	v_add_u32_e32 v2, 0xffffff88, v2
	v_cmp_lt_u32_e64 s[0:1], 63, v2
	s_nop 1
	v_cndmask_b32_e64 v19, 0, v23, s[0:1]
	v_add_u32_e32 v2, v19, v2
	v_cmp_lt_u32_e64 s[10:11], 31, v2
	s_nop 1
	v_cndmask_b32_e64 v19, 0, v24, s[10:11]
	v_add_u32_e32 v2, v19, v2
	v_cmp_lt_u32_e64 s[12:13], 31, v2
	s_nop 1
	v_cndmask_b32_e64 v19, 0, v24, s[12:13]
	v_add_u32_e32 v19, v19, v2
	v_and_b32_e32 v2, 0x7fffff, v18
	v_or_b32_e32 v44, 0x800000, v2
	v_mad_u64_u32 v[32:33], s[14:15], v44, s66, 0
	v_mov_b32_e32 v2, v33
	v_mad_u64_u32 v[34:35], s[14:15], v44, s67, v[2:3]
	v_mov_b32_e32 v2, v35
	v_mad_u64_u32 v[36:37], s[14:15], v44, s68, v[2:3]
	v_mov_b32_e32 v2, v37
	v_mad_u64_u32 v[38:39], s[14:15], v44, s69, v[2:3]
	v_mov_b32_e32 v2, v39
	v_mad_u64_u32 v[40:41], s[14:15], v44, s54, v[2:3]
	v_mov_b32_e32 v2, v41
	v_mad_u64_u32 v[42:43], s[14:15], v44, s78, v[2:3]
	v_mov_b32_e32 v2, v43
	v_mad_u64_u32 v[44:45], s[14:15], v44, s30, v[2:3]
	v_cndmask_b32_e64 v33, v42, v38, s[0:1]
	v_cndmask_b32_e64 v2, v44, v40, s[0:1]
	v_cndmask_b32_e64 v37, v45, v42, s[0:1]
	v_cndmask_b32_e64 v35, v2, v33, s[10:11]
	v_cndmask_b32_e64 v2, v37, v2, s[10:11]
	v_cndmask_b32_e64 v37, v40, v36, s[0:1]
	v_cndmask_b32_e64 v33, v33, v37, s[10:11]
	v_sub_u32_e32 v39, 32, v19
	v_cmp_eq_u32_e64 s[14:15], 0, v19
	v_cndmask_b32_e64 v19, v38, v34, s[0:1]
	v_cndmask_b32_e64 v2, v2, v35, s[12:13]
	v_cndmask_b32_e64 v35, v35, v33, s[12:13]
	v_cndmask_b32_e64 v34, v37, v19, s[10:11]
	v_alignbit_b32 v40, v2, v35, v39
	v_cndmask_b32_e64 v33, v33, v34, s[12:13]
	v_cndmask_b32_e64 v2, v40, v2, s[14:15]
	v_alignbit_b32 v37, v35, v33, v39
	v_cndmask_b32_e64 v32, v36, v32, s[0:1]
	v_cndmask_b32_e64 v35, v37, v35, s[14:15]
	v_bfe_u32 v40, v2, 29, 1
	v_cndmask_b32_e64 v19, v19, v32, s[10:11]
	v_alignbit_b32 v37, v2, v35, 30
	v_sub_u32_e32 v41, 0, v40
	v_cndmask_b32_e64 v19, v34, v19, s[12:13]
	v_xor_b32_e32 v37, v37, v41
	v_alignbit_b32 v32, v33, v19, v39
	v_cndmask_b32_e64 v32, v32, v33, s[14:15]
	v_ffbh_u32_e32 v34, v37
	v_alignbit_b32 v33, v35, v32, 30
	v_min_u32_e32 v34, 32, v34
	v_alignbit_b32 v19, v32, v19, 30
	v_xor_b32_e32 v33, v33, v41
	v_sub_u32_e32 v35, 31, v34
	v_xor_b32_e32 v19, v19, v41
	v_alignbit_b32 v36, v37, v33, v35
	v_alignbit_b32 v19, v33, v19, v35
	v_alignbit_b32 v32, v36, v19, 9
	v_ffbh_u32_e32 v33, v32
	v_min_u32_e32 v33, 32, v33
	v_lshrrev_b32_e32 v38, 29, v2
	v_not_b32_e32 v35, v33
	v_alignbit_b32 v19, v32, v19, v35
	v_lshlrev_b32_e32 v32, 31, v38
	v_or_b32_e32 v35, 0x33000000, v32
	v_add_lshl_u32 v33, v33, v34, 23
	v_lshrrev_b32_e32 v19, 9, v19
	v_sub_u32_e32 v33, v35, v33
	v_or_b32_e32 v32, 0.5, v32
	v_lshlrev_b32_e32 v34, 23, v34
	v_or_b32_e32 v19, v33, v19
	v_lshrrev_b32_e32 v33, 9, v36
	v_sub_u32_e32 v32, v32, v34
	v_or_b32_e32 v32, v33, v32
	v_mul_f32_e32 v33, 0x3fc90fda, v32
	v_fma_f32 v34, v32, s31, -v33
	v_fmac_f32_e32 v34, 0x33a22168, v32
	v_fmac_f32_e32 v34, 0x3fc90fda, v19
	v_lshrrev_b32_e32 v2, 30, v2
	v_add_f32_e32 v19, v33, v34
	v_add_u32_e32 v2, v40, v2
